# plus EpiUp: hoist 8 per-row stats loads to epilogue top, drop 7 vmcnt(0) drains
# speedup vs baseline: 1.0337x; 1.0152x over previous
; #define PG8_STAGE(bufoff, gbase, voff) do { _Pragma("unroll") for (int _i = 0; _i < 2; ++_i) \
;         __builtin_amdgcn_global_load_lds((const unsigned*)((const char*)(gbase) + (voff)[_i]), (LAS unsigned*)(lds + (bufoff) + ldsw + _i * 8192), 16, 0, 0); } while (0)
; #define PG8_LDA(dst, b, h) do { _Pragma("unroll") for (int m = 0; m < 4; ++m) _Pragma("unroll") for (int k = 0; k < 2; ++k) dst[m][k] = *(const LAS bf16x8*)(lds + PG8_SA(b, h) + aoff + m * 2048 + k * 1024); } while (0)
; #define PG8_LDB(dst, b, h) do { _Pragma("unroll") for (int n = 0; n < 2; ++n) _Pragma("unroll") for (int k = 0; k < 2; ++k) dst[n][k] = *(const LAS bf16x8*)(lds + PG8_SB(b, h) + boff + n * 2048 + k * 1024); } while (0)
; #define PG8_MMA(ai, bj, At, Bt) do { __builtin_amdgcn_s_setprio(1); _Pragma("unroll") for (int m = 0; m < 4; ++m) _Pragma("unroll") for (int n = 0; n < 2; ++n) _Pragma("unroll") for (int k = 0; k < 2; ++k) \
;         acc[ai][bj][m][n] = __builtin_amdgcn_mfma_f32_16x16x32_bf16(Bt[n][k], At[m][k], acc[ai][bj][m][n], 0, 0, 0); __builtin_amdgcn_s_setprio(0); } while (0)
; #define PG8_WAIT_L(n) asm volatile("s_waitcnt lgkmcnt(" #n ")" ::: "memory")
; #define PG8_BAR __builtin_amdgcn_s_barrier()
; #define PG8_SCHED __builtin_amdgcn_sched_barrier(0)
; template <class Epi>
; __device__ __forceinline__ void gemm_phase(const int TID, const int BID, LAS unsigned char* lds, const Gemm g, const StaticOrder& S, const Epi& E) {
;     ...
;             PG8_LDB(B0, 0, 0); PG8_SCHED; PG8_LDA(At, 0, 0); PG8_STAGE(PG8_SA(1, 1), a1 + hstepA, voffA);
;             PG8_WAIT_L(8); PG8_BAR; PG8_WAIT_L(0); PG8_MMA(0, 0, At, B0); PG8_BAR; PG8_SCHED;
;             PG8_LDB(B1, 0, 1); PG8_STAGE(PG8_SB(0, 0), b2, voffB);
;             PG8_BAR; PG8_WAIT_L(0); PG8_MMA(0, 1, At, B1); PG8_BAR;
;             PG8_LDA(At, 0, 1); PG8_STAGE(PG8_SA(0, 0), a2, voffA);
;             PG8_BAR; PG8_WAIT_L(0); PG8_MMA(1, 0, At, B0); PG8_BAR; PG8_SCHED;
.LBB0_925:
	v_add_u32_e32 v154, s31, v147
	ds_read_b128 v[138:141], v154
	ds_read_b128 v[142:145], v154 offset:1024
	ds_read_b128 v[150:153], v154 offset:2048
	ds_read_b128 v[154:157], v154 offset:3072
	s_add_u32 s36, s34, 0xfff80080
	s_addc_u32 s37, s35, -1
	s_cmp_eq_u32 s64, 28
	s_cselect_b32 s39, s1, s37
	s_cselect_b32 s38, s4, s36
	s_cselect_b32 s37, s17, s23
	s_cselect_b32 s36, s19, s22
	v_lshl_add_u64 v[158:159], s[34:35], 0, v[134:135]
	s_add_i32 m0, s48, 0xc000
	ds_read_b128 v[166:169], v149
	ds_read_b128 v[170:173], v149 offset:1024
	ds_read_b128 v[174:177], v149 offset:2048
	ds_read_b128 v[178:181], v149 offset:3072
	ds_read_b128 v[182:185], v149 offset:4096
	ds_read_b128 v[196:199], v149 offset:5120
	ds_read_b128 v[208:211], v149 offset:6144
	ds_read_b128 v[212:215], v149 offset:7168
	global_load_lds_dwordx4 v[158:159], off
	v_lshl_add_u64 v[158:159], s[34:35], 0, v[136:137]
	s_add_i32 m0, s48, 0xe000
	s_nop 0
	global_load_lds_dwordx4 v[158:159], off
	s_waitcnt lgkmcnt(8)
	s_barrier
	s_waitcnt lgkmcnt(0)
	s_setprio 1
	s_waitcnt lgkmcnt(0)
	v_mfma_f32_16x16x32_bf16 v[124:127], v[138:141], v[166:169], v[124:127]
	v_mfma_f32_16x16x32_bf16 v[120:123], v[150:153], v[166:169], v[120:123]
	v_mfma_f32_16x16x32_bf16 v[108:111], v[138:141], v[174:177], v[108:111]
	v_mfma_f32_16x16x32_bf16 v[104:107], v[150:153], v[174:177], v[104:107]
	v_mfma_f32_16x16x32_bf16 v[92:95], v[138:141], v[182:185], v[92:95]
	v_mfma_f32_16x16x32_bf16 v[88:91], v[150:153], v[182:185], v[88:91]
	v_mfma_f32_16x16x32_bf16 v[76:79], v[138:141], v[208:211], v[76:79]
	v_mfma_f32_16x16x32_bf16 v[72:75], v[150:153], v[208:211], v[72:75]
	v_mfma_f32_16x16x32_bf16 v[124:127], v[142:145], v[170:173], v[124:127]
	v_mfma_f32_16x16x32_bf16 v[120:123], v[154:157], v[170:173], v[120:123]
	v_mfma_f32_16x16x32_bf16 v[108:111], v[142:145], v[178:181], v[108:111]
	v_mfma_f32_16x16x32_bf16 v[104:107], v[154:157], v[178:181], v[104:107]
	v_mfma_f32_16x16x32_bf16 v[92:95], v[142:145], v[196:199], v[92:95]
	v_mfma_f32_16x16x32_bf16 v[88:91], v[154:157], v[196:199], v[88:91]
	v_mfma_f32_16x16x32_bf16 v[76:79], v[142:145], v[212:215], v[76:79]
	v_mfma_f32_16x16x32_bf16 v[72:75], v[154:157], v[212:215], v[72:75]
	s_setprio 0
	s_barrier
	v_add_u32_e32 v158, s50, v147
	s_mov_b32 m0, s46
	ds_read_b128 v[216:219], v158
	ds_read_b128 v[220:223], v158 offset:1024
	ds_read_b128 v[224:227], v158 offset:2048
	ds_read_b128 v[228:231], v158 offset:3072
	v_lshl_add_u64 v[158:159], s[36:37], 0, v[160:161]
	global_load_lds_dwordx4 v[158:159], off
	v_lshl_add_u64 v[200:201], s[36:37], 0, v[132:133]
	s_mov_b32 m0, s47
	s_nop 0
	global_load_lds_dwordx4 v[200:201], off
	s_barrier
	s_waitcnt lgkmcnt(0)
	s_setprio 1
	s_waitcnt lgkmcnt(0)
	v_mfma_f32_16x16x32_bf16 v[116:119], v[216:219], v[166:169], v[116:119]
	v_mfma_f32_16x16x32_bf16 v[112:115], v[224:227], v[166:169], v[112:115]
	v_mfma_f32_16x16x32_bf16 v[100:103], v[216:219], v[174:177], v[100:103]
	v_mfma_f32_16x16x32_bf16 v[96:99], v[224:227], v[174:177], v[96:99]
	v_mfma_f32_16x16x32_bf16 v[84:87], v[216:219], v[182:185], v[84:87]
	v_mfma_f32_16x16x32_bf16 v[80:83], v[224:227], v[182:185], v[80:83]
	v_mfma_f32_16x16x32_bf16 v[68:71], v[216:219], v[208:211], v[68:71]
	v_mfma_f32_16x16x32_bf16 v[64:67], v[224:227], v[208:211], v[64:67]
	v_mfma_f32_16x16x32_bf16 v[116:119], v[220:223], v[170:173], v[116:119]
	v_mfma_f32_16x16x32_bf16 v[112:115], v[228:231], v[170:173], v[112:115]
	v_mfma_f32_16x16x32_bf16 v[100:103], v[220:223], v[178:181], v[100:103]
	v_mfma_f32_16x16x32_bf16 v[96:99], v[228:231], v[178:181], v[96:99]
	v_mfma_f32_16x16x32_bf16 v[84:87], v[220:223], v[196:199], v[84:87]
	v_mfma_f32_16x16x32_bf16 v[80:83], v[228:231], v[196:199], v[80:83]
	v_mfma_f32_16x16x32_bf16 v[68:71], v[220:223], v[212:215], v[68:71]
	v_mfma_f32_16x16x32_bf16 v[64:67], v[228:231], v[212:215], v[64:67]
	s_setprio 0
	s_mov_b32 m0, s48
	v_lshl_add_u64 v[232:233], s[38:39], 0, v[128:129]
	s_barrier
	ds_read_b128 v[166:169], v149 offset:16384
	ds_read_b128 v[170:173], v149 offset:17408
	ds_read_b128 v[174:177], v149 offset:18432
	ds_read_b128 v[178:181], v149 offset:19456
	ds_read_b128 v[182:185], v149 offset:20480
	ds_read_b128 v[196:199], v149 offset:21504
	ds_read_b128 v[208:211], v149 offset:22528
	ds_read_b128 v[212:215], v149 offset:23552
	global_load_lds_dwordx4 v[232:233], off
	v_lshl_add_u64 v[234:235], s[38:39], 0, v[130:131]
	s_mov_b32 m0, s49
	s_nop 0
	global_load_lds_dwordx4 v[234:235], off
	s_barrier
	s_waitcnt lgkmcnt(0)
	s_setprio 1
	s_waitcnt lgkmcnt(0)
	v_mfma_f32_16x16x32_bf16 v[60:63], v[138:141], v[166:169], v[60:63]
	v_mfma_f32_16x16x32_bf16 v[56:59], v[150:153], v[166:169], v[56:59]
	v_mfma_f32_16x16x32_bf16 v[44:47], v[138:141], v[174:177], v[44:47]
	v_mfma_f32_16x16x32_bf16 v[40:43], v[150:153], v[174:177], v[40:43]
	v_mfma_f32_16x16x32_bf16 v[28:31], v[138:141], v[182:185], v[28:31]
	v_mfma_f32_16x16x32_bf16 v[24:27], v[150:153], v[182:185], v[24:27]
	v_mfma_f32_16x16x32_bf16 v[12:15], v[138:141], v[208:211], v[12:15]
	v_mfma_f32_16x16x32_bf16 v[8:11], v[150:153], v[208:211], v[8:11]
	v_mfma_f32_16x16x32_bf16 v[60:63], v[142:145], v[170:173], v[60:63]
	v_mfma_f32_16x16x32_bf16 v[56:59], v[154:157], v[170:173], v[56:59]
	v_mfma_f32_16x16x32_bf16 v[44:47], v[142:145], v[178:181], v[44:47]
	v_mfma_f32_16x16x32_bf16 v[40:43], v[154:157], v[178:181], v[40:43]
	v_mfma_f32_16x16x32_bf16 v[28:31], v[142:145], v[196:199], v[28:31]
	v_mfma_f32_16x16x32_bf16 v[24:27], v[154:157], v[196:199], v[24:27]
	v_mfma_f32_16x16x32_bf16 v[12:15], v[142:145], v[212:215], v[12:15]
	v_mfma_f32_16x16x32_bf16 v[8:11], v[154:157], v[212:215], v[8:11]
	s_setprio 0
	s_barrier
; #define PG8_STAGE(bufoff, gbase, voff) do { _Pragma("unroll") for (int _i = 0; _i < 2; ++_i) \
;         __builtin_amdgcn_global_load_lds((const unsigned*)((const char*)(gbase) + (voff)[_i]), (LAS unsigned*)(lds + (bufoff) + ldsw + _i * 8192), 16, 0, 0); } while (0)
; #define PG8_LDA(dst, b, h) do { _Pragma("unroll") for (int m = 0; m < 4; ++m) _Pragma("unroll") for (int k = 0; k < 2; ++k) dst[m][k] = *(const LAS bf16x8*)(lds + PG8_SA(b, h) + aoff + m * 2048 + k * 1024); } while (0)
; #define PG8_LDB(dst, b, h) do { _Pragma("unroll") for (int n = 0; n < 2; ++n) _Pragma("unroll") for (int k = 0; k < 2; ++k) dst[n][k] = *(const LAS bf16x8*)(lds + PG8_SB(b, h) + boff + n * 2048 + k * 1024); } while (0)
; #define PG8_MMA(ai, bj, At, Bt) do { __builtin_amdgcn_s_setprio(1); _Pragma("unroll") for (int m = 0; m < 4; ++m) _Pragma("unroll") for (int n = 0; n < 2; ++n) _Pragma("unroll") for (int k = 0; k < 2; ++k) \
;         acc[ai][bj][m][n] = __builtin_amdgcn_mfma_f32_16x16x32_bf16(Bt[n][k], At[m][k], acc[ai][bj][m][n], 0, 0, 0); __builtin_amdgcn_s_setprio(0); } while (0)
; #define PG8_WAIT_V(n) asm volatile("s_waitcnt vmcnt(" #n ")" ::: "memory")
; #define PG8_WAIT_L(n) asm volatile("s_waitcnt lgkmcnt(" #n ")" ::: "memory")
; #define PG8_BAR __builtin_amdgcn_s_barrier()
; #define PG8_SCHED __builtin_amdgcn_sched_barrier(0)
; template <class Epi>
; __device__ __forceinline__ void gemm_phase(const int TID, const int BID, LAS unsigned char* lds, const Gemm g, const StaticOrder& S, const Epi& E) {
;     ...
;             PG8_STAGE(PG8_SB(0, 1), b2 + hstepB, voffB);
;             PG8_WAIT_V(6); PG8_BAR; PG8_MMA(1, 1, At, B1); PG8_BAR;
;             PG8_LDB(B0, 1, 0); PG8_SCHED; PG8_LDA(At, 1, 0); PG8_STAGE(PG8_SA(0, 1), a2 + hstepA, voffA);
;             PG8_WAIT_L(8); PG8_BAR; PG8_WAIT_L(0); PG8_MMA(0, 0, At, B0); PG8_BAR; PG8_SCHED;
;             PG8_LDB(B1, 1, 1); PG8_STAGE(PG8_SB(1, 0), b3, voffB);
;             PG8_BAR; PG8_WAIT_L(0); PG8_MMA(0, 1, At, B1); PG8_BAR;
;             PG8_LDA(At, 1, 1); PG8_STAGE(PG8_SA(1, 0), a3, voffA);
	s_add_u32 s66, s36, 0x80000
	s_addc_u32 s67, s37, 0
	s_mov_b32 m0, s51
	v_lshl_add_u64 v[138:139], s[66:67], 0, v[160:161]
	global_load_lds_dwordx4 v[138:139], off
	v_lshl_add_u64 v[138:139], s[66:67], 0, v[132:133]
	s_mov_b32 m0, s52
	s_nop 0
	global_load_lds_dwordx4 v[138:139], off
	s_waitcnt vmcnt(6)
	s_barrier
	s_setprio 1
	v_mfma_f32_16x16x32_bf16 v[52:55], v[216:219], v[166:169], v[52:55]
	v_mfma_f32_16x16x32_bf16 v[48:51], v[224:227], v[166:169], v[48:51]
	v_mfma_f32_16x16x32_bf16 v[36:39], v[216:219], v[174:177], v[36:39]
	v_mfma_f32_16x16x32_bf16 v[32:35], v[224:227], v[174:177], v[32:35]
	v_mfma_f32_16x16x32_bf16 v[20:23], v[216:219], v[182:185], v[20:23]
	v_mfma_f32_16x16x32_bf16 v[16:19], v[224:227], v[182:185], v[16:19]
	v_mfma_f32_16x16x32_bf16 v[4:7], v[216:219], v[208:211], v[4:7]
	v_mfma_f32_16x16x32_bf16 v[0:3], v[224:227], v[208:211], v[0:3]
	v_mfma_f32_16x16x32_bf16 v[52:55], v[220:223], v[170:173], v[52:55]
	v_mfma_f32_16x16x32_bf16 v[48:51], v[228:231], v[170:173], v[48:51]
	v_mfma_f32_16x16x32_bf16 v[36:39], v[220:223], v[178:181], v[36:39]
	v_mfma_f32_16x16x32_bf16 v[32:35], v[228:231], v[178:181], v[32:35]
	v_mfma_f32_16x16x32_bf16 v[20:23], v[220:223], v[196:199], v[20:23]
	v_mfma_f32_16x16x32_bf16 v[16:19], v[228:231], v[196:199], v[16:19]
	v_mfma_f32_16x16x32_bf16 v[4:7], v[220:223], v[212:215], v[4:7]
	v_mfma_f32_16x16x32_bf16 v[0:3], v[228:231], v[212:215], v[0:3]
	s_setprio 0
	v_add_u32_e32 v154, s55, v147
	s_barrier
	ds_read_b128 v[138:141], v154
	ds_read_b128 v[142:145], v154 offset:1024
	ds_read_b128 v[150:153], v154 offset:2048
	ds_read_b128 v[154:157], v154 offset:3072
	s_add_u32 s38, s38, 0x80000
	s_addc_u32 s39, s39, 0
	s_mov_b32 m0, s53
	v_lshl_add_u64 v[216:217], s[38:39], 0, v[128:129]
	ds_read_b128 v[166:169], v149 offset:32768
	ds_read_b128 v[170:173], v149 offset:33792
	ds_read_b128 v[174:177], v149 offset:34816
	ds_read_b128 v[178:181], v149 offset:35840
	ds_read_b128 v[182:185], v149 offset:36864
	ds_read_b128 v[196:199], v149 offset:37888
	ds_read_b128 v[208:211], v149 offset:38912
	ds_read_b128 v[212:215], v149 offset:39936
	global_load_lds_dwordx4 v[216:217], off
	v_lshl_add_u64 v[216:217], s[38:39], 0, v[130:131]
	s_mov_b32 m0, s54
	s_nop 0
	global_load_lds_dwordx4 v[216:217], off
	s_waitcnt lgkmcnt(8)
	s_barrier
	s_waitcnt lgkmcnt(0)
	s_setprio 1
	s_waitcnt lgkmcnt(0)
	v_mfma_f32_16x16x32_bf16 v[124:127], v[138:141], v[166:169], v[124:127]
	v_mfma_f32_16x16x32_bf16 v[120:123], v[150:153], v[166:169], v[120:123]
	v_mfma_f32_16x16x32_bf16 v[108:111], v[138:141], v[174:177], v[108:111]
	v_mfma_f32_16x16x32_bf16 v[104:107], v[150:153], v[174:177], v[104:107]
	v_mfma_f32_16x16x32_bf16 v[92:95], v[138:141], v[182:185], v[92:95]
	v_mfma_f32_16x16x32_bf16 v[88:91], v[150:153], v[182:185], v[88:91]
	v_mfma_f32_16x16x32_bf16 v[76:79], v[138:141], v[208:211], v[76:79]
	v_mfma_f32_16x16x32_bf16 v[72:75], v[150:153], v[208:211], v[72:75]
	v_mfma_f32_16x16x32_bf16 v[124:127], v[142:145], v[170:173], v[124:127]
	v_mfma_f32_16x16x32_bf16 v[120:123], v[154:157], v[170:173], v[120:123]
	v_mfma_f32_16x16x32_bf16 v[108:111], v[142:145], v[178:181], v[108:111]
	v_mfma_f32_16x16x32_bf16 v[104:107], v[154:157], v[178:181], v[104:107]
	v_mfma_f32_16x16x32_bf16 v[92:95], v[142:145], v[196:199], v[92:95]
	v_mfma_f32_16x16x32_bf16 v[88:91], v[154:157], v[196:199], v[88:91]
	v_mfma_f32_16x16x32_bf16 v[76:79], v[142:145], v[212:215], v[76:79]
	v_mfma_f32_16x16x32_bf16 v[72:75], v[154:157], v[212:215], v[72:75]
	s_setprio 0
	s_barrier
	s_mov_b32 m0, s56
	v_add_u32_e32 v228, s60, v147
	v_lshl_add_u64 v[158:159], v[158:159], 0, s[90:91]
	ds_read_b128 v[216:219], v228
	ds_read_b128 v[220:223], v228 offset:1024
	ds_read_b128 v[224:227], v228 offset:2048
	ds_read_b128 v[228:231], v228 offset:3072
	global_load_lds_dwordx4 v[158:159], off
	v_lshl_add_u64 v[158:159], v[200:201], 0, s[90:91]
	s_mov_b32 m0, s57
	s_nop 0
	global_load_lds_dwordx4 v[158:159], off
	s_barrier
	s_waitcnt lgkmcnt(0)
	s_setprio 1
	s_waitcnt lgkmcnt(0)
	v_mfma_f32_16x16x32_bf16 v[116:119], v[216:219], v[166:169], v[116:119]
	v_mfma_f32_16x16x32_bf16 v[112:115], v[224:227], v[166:169], v[112:115]
	v_mfma_f32_16x16x32_bf16 v[100:103], v[216:219], v[174:177], v[100:103]
	v_mfma_f32_16x16x32_bf16 v[96:99], v[224:227], v[174:177], v[96:99]
	v_mfma_f32_16x16x32_bf16 v[84:87], v[216:219], v[182:185], v[84:87]
	v_mfma_f32_16x16x32_bf16 v[80:83], v[224:227], v[182:185], v[80:83]
	v_mfma_f32_16x16x32_bf16 v[68:71], v[216:219], v[208:211], v[68:71]
	v_mfma_f32_16x16x32_bf16 v[64:67], v[224:227], v[208:211], v[64:67]
	v_mfma_f32_16x16x32_bf16 v[116:119], v[220:223], v[170:173], v[116:119]
	v_mfma_f32_16x16x32_bf16 v[112:115], v[228:231], v[170:173], v[112:115]
	v_mfma_f32_16x16x32_bf16 v[100:103], v[220:223], v[178:181], v[100:103]
	v_mfma_f32_16x16x32_bf16 v[96:99], v[228:231], v[178:181], v[96:99]
	v_mfma_f32_16x16x32_bf16 v[84:87], v[220:223], v[196:199], v[84:87]
	v_mfma_f32_16x16x32_bf16 v[80:83], v[228:231], v[196:199], v[80:83]
	v_mfma_f32_16x16x32_bf16 v[68:71], v[220:223], v[212:215], v[68:71]
	v_mfma_f32_16x16x32_bf16 v[64:67], v[228:231], v[212:215], v[64:67]
	s_setprio 0
	s_mov_b32 m0, s58
	v_lshl_add_u64 v[158:159], v[232:233], 0, s[90:91]
	s_barrier
	ds_read_b128 v[166:169], v149 offset:49152
	ds_read_b128 v[170:173], v149 offset:50176
	ds_read_b128 v[174:177], v149 offset:51200
	ds_read_b128 v[178:181], v149 offset:52224
	ds_read_b128 v[182:185], v149 offset:53248
	ds_read_b128 v[196:199], v149 offset:54272
	ds_read_b128 v[208:211], v149 offset:55296
	ds_read_b128 v[212:215], v149 offset:56320
	global_load_lds_dwordx4 v[158:159], off
	v_lshl_add_u64 v[158:159], v[234:235], 0, s[90:91]
	s_mov_b32 m0, s59
	s_nop 0
	global_load_lds_dwordx4 v[158:159], off
	s_barrier
; __device__ __forceinline__ unsigned cvt_pk_bf16(float lo, float hi) { unsigned r; asm volatile("v_cvt_pk_bf16_f32 %0, %1, %2" : "=v"(r) : "v"(lo), "v"(hi)); return r; }
; __device__ __forceinline__ float rinv_st(stat_t s, float invn) { return rsqrtf((float)((double)s * (1.0 / 4294967296.0)) * invn + 1e-6f); }
; #define PG8_STAGE(bufoff, gbase, voff) do { _Pragma("unroll") for (int _i = 0; _i < 2; ++_i) \
;         __builtin_amdgcn_global_load_lds((const unsigned*)((const char*)(gbase) + (voff)[_i]), (LAS unsigned*)(lds + (bufoff) + ldsw + _i * 8192), 16, 0, 0); } while (0)
; #define PG8_MMA(ai, bj, At, Bt) do { __builtin_amdgcn_s_setprio(1); _Pragma("unroll") for (int m = 0; m < 4; ++m) _Pragma("unroll") for (int n = 0; n < 2; ++n) _Pragma("unroll") for (int k = 0; k < 2; ++k) \
;         acc[ai][bj][m][n] = __builtin_amdgcn_mfma_f32_16x16x32_bf16(Bt[n][k], At[m][k], acc[ai][bj][m][n], 0, 0, 0); __builtin_amdgcn_s_setprio(0); } while (0)
; #define PG8_WAIT_V(n) asm volatile("s_waitcnt vmcnt(" #n ")" ::: "memory")
; #define PG8_WAIT_L(n) asm volatile("s_waitcnt lgkmcnt(" #n ")" ::: "memory")
; #define PG8_BAR __builtin_amdgcn_s_barrier()
; template <class Epi>
; __device__ __forceinline__ void gemm_phase(const int TID, const int BID, LAS unsigned char* lds, const Gemm g, const StaticOrder& S, const Epi& E) {
;     ...
;             PG8_BAR; PG8_WAIT_L(0); PG8_MMA(1, 0, At, B0); PG8_BAR; PG8_SCHED;
;             PG8_STAGE(PG8_SB(1, 1), b3 + hstepB, voffB);
;             PG8_WAIT_V(6); PG8_BAR; PG8_MMA(1, 1, At, B1); PG8_BAR;
;         }
;     __device__ __forceinline__ void operator()(const f32x4 (&acc)[2][2][4][2], const Unit& u, int wr, int wc, int fr, int fq) const {
;     ...
;                 const int row = row0 + ai * HALF + m * 16; const float r = rinv_st(stats[row], 1.0f / 2048.0f);
;                 bf16_t* rowp = U + (size_t)row * FF + col0;
; #pragma unroll
;                 for (int bj = 0; bj < 2; ++bj) {
;                     f32x4 v0 = acc[ai][bj][m][0] * r, v1 = acc[ai][bj][m][1] * r;
; #pragma unroll
;                     for (int j = 0; j < 4; ++j) { const float a = fmaxf(v0[j], 0.f), b = fmaxf(v1[j], 0.f); v0[j] = a * a; v1[j] = b * b; }
;                     u32x4 w; w.x = cvt_pk_bf16(v0[0], v0[1]); w.y = cvt_pk_bf16(v0[2], v0[3]); w.z = cvt_pk_bf16(v1[0], v1[1]); w.w = cvt_pk_bf16(v1[2], v1[3]);
;                     *(u32x4*)(rowp + bj * HALF) = w;
	s_waitcnt lgkmcnt(0)
	s_setprio 1
	s_waitcnt lgkmcnt(0)
	v_mfma_f32_16x16x32_bf16 v[60:63], v[138:141], v[166:169], v[60:63]
	v_mfma_f32_16x16x32_bf16 v[56:59], v[150:153], v[166:169], v[56:59]
	v_mfma_f32_16x16x32_bf16 v[44:47], v[138:141], v[174:177], v[44:47]
	v_mfma_f32_16x16x32_bf16 v[40:43], v[150:153], v[174:177], v[40:43]
	v_mfma_f32_16x16x32_bf16 v[28:31], v[138:141], v[182:185], v[28:31]
	v_mfma_f32_16x16x32_bf16 v[24:27], v[150:153], v[182:185], v[24:27]
	v_mfma_f32_16x16x32_bf16 v[12:15], v[138:141], v[208:211], v[12:15]
	v_mfma_f32_16x16x32_bf16 v[8:11], v[150:153], v[208:211], v[8:11]
	v_mfma_f32_16x16x32_bf16 v[60:63], v[142:145], v[170:173], v[60:63]
	v_mfma_f32_16x16x32_bf16 v[56:59], v[154:157], v[170:173], v[56:59]
	v_mfma_f32_16x16x32_bf16 v[44:47], v[142:145], v[178:181], v[44:47]
	v_mfma_f32_16x16x32_bf16 v[40:43], v[154:157], v[178:181], v[40:43]
	v_mfma_f32_16x16x32_bf16 v[28:31], v[142:145], v[196:199], v[28:31]
	v_mfma_f32_16x16x32_bf16 v[24:27], v[154:157], v[196:199], v[24:27]
	v_mfma_f32_16x16x32_bf16 v[12:15], v[142:145], v[212:215], v[12:15]
	v_mfma_f32_16x16x32_bf16 v[8:11], v[154:157], v[212:215], v[8:11]
	s_setprio 0
	s_barrier
	s_add_u32 s36, s36, 0x80080
	s_addc_u32 s37, s37, 0
	s_mov_b32 m0, s61
	v_lshl_add_u64 v[138:139], s[36:37], 0, v[160:161]
	global_load_lds_dwordx4 v[138:139], off
	v_lshl_add_u64 v[138:139], s[36:37], 0, v[132:133]
	s_mov_b32 m0, s62
	s_nop 0
	global_load_lds_dwordx4 v[138:139], off
	s_waitcnt vmcnt(6)
	s_barrier
	s_setprio 1
	v_mfma_f32_16x16x32_bf16 v[52:55], v[216:219], v[166:169], v[52:55]
	v_mfma_f32_16x16x32_bf16 v[48:51], v[224:227], v[166:169], v[48:51]
	v_mfma_f32_16x16x32_bf16 v[36:39], v[216:219], v[174:177], v[36:39]
	v_mfma_f32_16x16x32_bf16 v[32:35], v[224:227], v[174:177], v[32:35]
	v_mfma_f32_16x16x32_bf16 v[20:23], v[216:219], v[182:185], v[20:23]
	v_mfma_f32_16x16x32_bf16 v[16:19], v[224:227], v[182:185], v[16:19]
	v_mfma_f32_16x16x32_bf16 v[4:7], v[216:219], v[208:211], v[4:7]
	v_mfma_f32_16x16x32_bf16 v[0:3], v[224:227], v[208:211], v[0:3]
	v_mfma_f32_16x16x32_bf16 v[52:55], v[220:223], v[170:173], v[52:55]
	v_mfma_f32_16x16x32_bf16 v[48:51], v[228:231], v[170:173], v[48:51]
	v_mfma_f32_16x16x32_bf16 v[36:39], v[220:223], v[178:181], v[36:39]
	v_mfma_f32_16x16x32_bf16 v[32:35], v[228:231], v[178:181], v[32:35]
	v_mfma_f32_16x16x32_bf16 v[20:23], v[220:223], v[196:199], v[20:23]
	v_mfma_f32_16x16x32_bf16 v[16:19], v[228:231], v[196:199], v[16:19]
	v_mfma_f32_16x16x32_bf16 v[4:7], v[220:223], v[212:215], v[4:7]
	v_mfma_f32_16x16x32_bf16 v[0:3], v[228:231], v[212:215], v[0:3]
	s_setprio 0
	s_add_i32 s64, s64, 2
	s_add_u32 s34, s34, 0x100
	s_addc_u32 s35, s35, 0
	s_add_u32 s22, s22, 0x100
	s_addc_u32 s23, s23, 0
	s_cmp_gt_u32 s64, 29
	s_barrier
	s_cbranch_scc0 .LBB0_925
	v_lshl_add_u32 v142, s30, 8, v146
	v_ashrrev_i32_e32 v143, 31, v142
	v_lshl_add_u64 v[138:139], v[142:143], 3, s[10:11]
	global_load_dwordx2 v[144:145], v[138:139], off
	global_load_dwordx2 v[208:209], v[138:139], off offset:128
	global_load_dwordx2 v[210:211], v[138:139], off offset:256
	global_load_dwordx2 v[212:213], v[138:139], off offset:384
	global_load_dwordx2 v[214:215], v[138:139], off offset:1024
	global_load_dwordx2 v[216:217], v[138:139], off offset:1152
	global_load_dwordx2 v[218:219], v[138:139], off offset:1280
	global_load_dwordx2 v[220:221], v[138:139], off offset:1408
	v_lshl_or_b32 v140, s0, 8, v148
	v_ashrrev_i32_e32 v141, 31, v140
	s_mov_b64 s[0:1], 0x200000
	s_mov_b32 s30, s18
	s_mov_b64 s[36:37], s[28:29]
	s_mov_b64 s[34:35], s[26:27]
	s_waitcnt vmcnt(0)
	v_cvt_f64_u32_e32 v[150:151], v145
	v_ldexp_f64 v[150:151], v[150:151], 32
	v_cvt_f64_u32_e32 v[144:145], v144
	v_add_f64 v[144:145], v[150:151], v[144:145]
	v_ldexp_f64 v[144:145], v[144:145], s93
	v_cvt_f32_f64_e32 v144, v[144:145]
	v_fmamk_f32 v144, v144, 0x3a000000, v189
	v_cmp_gt_f32_e32 vcc, s78, v144
	v_mul_f32_e32 v145, 0x4b800000, v144
	s_nop 0
	v_cndmask_b32_e32 v144, v144, v145, vcc
	v_rsq_f32_e32 v144, v144
	s_nop 0
	v_mul_f32_e32 v145, 0x45800000, v144
	v_cndmask_b32_e32 v150, v144, v145, vcc
	v_pk_mul_f32 v[120:121], v[120:121], v[150:151] op_sel_hi:[1,0]
	v_pk_mul_f32 v[124:125], v[124:125], v[150:151] op_sel_hi:[1,0]
	v_pk_mul_f32 v[122:123], v[122:123], v[150:151] op_sel_hi:[1,0]
	v_max_f32_e32 v120, 0, v120
	v_lshlrev_b64 v[144:145], 14, v[142:143]
	v_pk_mul_f32 v[126:127], v[126:127], v[150:151] op_sel_hi:[1,0]
	v_mul_f32_e32 v143, v120, v120
	v_max_f32_e32 v120, 0, v125
	v_max_f32_e32 v121, 0, v121
	v_max_f32_e32 v122, 0, v122
	v_lshl_add_u64 v[152:153], s[14:15], 0, v[144:145]
	v_lshlrev_b64 v[144:145], 1, v[140:141]
	v_max_f32_e32 v124, 0, v124
	v_mul_f32_e32 v120, v120, v120
	v_mul_f32_e32 v125, v121, v121
	v_max_f32_e32 v121, 0, v126
	v_mul_f32_e32 v126, v122, v122
	v_max_f32_e32 v122, 0, v127
	v_max_f32_e32 v123, 0, v123
	v_pk_mul_f32 v[114:115], v[114:115], v[150:151] op_sel_hi:[1,0]
	v_pk_mul_f32 v[112:113], v[112:113], v[150:151] op_sel_hi:[1,0]
	v_lshl_add_u64 v[140:141], v[152:153], 0, v[144:145]
	v_mul_f32_e32 v124, v124, v124
	v_mul_f32_e32 v121, v121, v121
	v_mul_f32_e32 v122, v122, v122
	v_mul_f32_e32 v123, v123, v123
	v_cvt_pk_bf16_f32 v120, v124, v120
	v_pk_mul_f32 v[118:119], v[118:119], v[150:151] op_sel_hi:[1,0]
	v_pk_mul_f32 v[116:117], v[116:117], v[150:151] op_sel_hi:[1,0]
	v_max_f32_e32 v112, 0, v112
	v_max_f32_e32 v113, 0, v113
	v_max_f32_e32 v114, 0, v114
	v_cvt_pk_bf16_f32 v121, v121, v122
	v_cvt_pk_bf16_f32 v122, v143, v125
	v_cvt_pk_bf16_f32 v123, v126, v123
	global_store_dwordx4 v[140:141], v[120:123], off
	v_max_f32_e32 v115, 0, v115
	v_max_f32_e32 v116, 0, v116
; __device__ __forceinline__ unsigned cvt_pk_bf16(float lo, float hi) { unsigned r; asm volatile("v_cvt_pk_bf16_f32 %0, %1, %2" : "=v"(r) : "v"(lo), "v"(hi)); return r; }
; __device__ __forceinline__ float rinv_st(stat_t s, float invn) { return rsqrtf((float)((double)s * (1.0 / 4294967296.0)) * invn + 1e-6f); }
;     __device__ __forceinline__ void operator()(const f32x4 (&acc)[2][2][4][2], const Unit& u, int wr, int wc, int fr, int fq) const {
;     ...
;             for (int m = 0; m < 4; ++m) {
;                 const int row = row0 + ai * HALF + m * 16; const float r = rinv_st(stats[row], 1.0f / 2048.0f);
;                 bf16_t* rowp = U + (size_t)row * FF + col0;
; #pragma unroll
;                 for (int bj = 0; bj < 2; ++bj) {
;                     f32x4 v0 = acc[ai][bj][m][0] * r, v1 = acc[ai][bj][m][1] * r;
; #pragma unroll
;                     for (int j = 0; j < 4; ++j) { const float a = fmaxf(v0[j], 0.f), b = fmaxf(v1[j], 0.f); v0[j] = a * a; v1[j] = b * b; }
;                     u32x4 w; w.x = cvt_pk_bf16(v0[0], v0[1]); w.y = cvt_pk_bf16(v0[2], v0[3]); w.z = cvt_pk_bf16(v1[0], v1[1]); w.w = cvt_pk_bf16(v1[2], v1[3]);
;                     *(u32x4*)(rowp + bj * HALF) = w;
;                 }
	v_mul_f32_e32 v120, v112, v112
	v_max_f32_e32 v112, 0, v117
	v_mul_f32_e32 v117, v113, v113
	v_max_f32_e32 v113, 0, v118
	v_mul_f32_e32 v118, v114, v114
	v_max_f32_e32 v114, 0, v119
	v_mul_f32_e32 v112, v112, v112
	v_mul_f32_e32 v113, v113, v113
	v_mul_f32_e32 v114, v114, v114
	v_mul_f32_e32 v115, v115, v115
	v_mul_f32_e32 v116, v116, v116
	v_cvt_pk_bf16_f32 v112, v116, v112
	v_cvt_pk_bf16_f32 v113, v113, v114
	v_cvt_pk_bf16_f32 v114, v120, v117
	v_cvt_pk_bf16_f32 v115, v118, v115
	global_store_dwordx4 v[140:141], v[112:115], off offset:256
	s_nop 1
	v_mov_b64_e32 v[114:115], v[208:209]
	v_cvt_f64_u32_e32 v[116:117], v115
	v_ldexp_f64 v[116:117], v[116:117], 32
	v_cvt_f64_u32_e32 v[114:115], v114
	v_add_f64 v[114:115], v[116:117], v[114:115]
	v_ldexp_f64 v[114:115], v[114:115], s93
	v_cvt_f32_f64_e32 v114, v[114:115]
	v_fmamk_f32 v114, v114, 0x3a000000, v189
	v_cmp_gt_f32_e32 vcc, s78, v114
	v_mul_f32_e32 v115, 0x4b800000, v114
	v_or_b32_e32 v112, 16, v142
	v_cndmask_b32_e32 v114, v114, v115, vcc
	v_rsq_f32_e32 v114, v114
	v_ashrrev_i32_e32 v113, 31, v112
	v_lshlrev_b64 v[112:113], 14, v[112:113]
	v_lshl_add_u64 v[112:113], s[14:15], 0, v[112:113]
	v_mul_f32_e32 v115, 0x45800000, v114
	v_cndmask_b32_e32 v114, v114, v115, vcc
	v_pk_mul_f32 v[104:105], v[104:105], v[114:115] op_sel_hi:[1,0]
	v_pk_mul_f32 v[108:109], v[108:109], v[114:115] op_sel_hi:[1,0]
	v_pk_mul_f32 v[106:107], v[106:107], v[114:115] op_sel_hi:[1,0]
	v_max_f32_e32 v104, 0, v104
	v_pk_mul_f32 v[110:111], v[110:111], v[114:115] op_sel_hi:[1,0]
	v_mul_f32_e32 v115, v104, v104
	v_max_f32_e32 v104, 0, v109
	v_max_f32_e32 v105, 0, v105
	v_max_f32_e32 v106, 0, v106
	v_max_f32_e32 v108, 0, v108
	v_mul_f32_e32 v104, v104, v104
	v_mul_f32_e32 v109, v105, v105
	v_max_f32_e32 v105, 0, v110
	v_mul_f32_e32 v110, v106, v106
	v_max_f32_e32 v106, 0, v111
	v_max_f32_e32 v107, 0, v107
	v_pk_mul_f32 v[98:99], v[98:99], v[114:115] op_sel_hi:[1,0]
	v_pk_mul_f32 v[96:97], v[96:97], v[114:115] op_sel_hi:[1,0]
	v_lshl_add_u64 v[112:113], v[112:113], 0, v[144:145]
	v_mul_f32_e32 v108, v108, v108
	v_mul_f32_e32 v105, v105, v105
	v_mul_f32_e32 v106, v106, v106
	v_mul_f32_e32 v107, v107, v107
	v_cvt_pk_bf16_f32 v104, v108, v104
	v_pk_mul_f32 v[102:103], v[102:103], v[114:115] op_sel_hi:[1,0]
	v_pk_mul_f32 v[100:101], v[100:101], v[114:115] op_sel_hi:[1,0]
	v_max_f32_e32 v96, 0, v96
	v_max_f32_e32 v97, 0, v97
	v_max_f32_e32 v98, 0, v98
	v_cvt_pk_bf16_f32 v105, v105, v106
	v_cvt_pk_bf16_f32 v106, v115, v109
	v_cvt_pk_bf16_f32 v107, v110, v107
	global_store_dwordx4 v[112:113], v[104:107], off
	v_max_f32_e32 v99, 0, v99
	v_max_f32_e32 v100, 0, v100
	v_mul_f32_e32 v104, v96, v96
	v_max_f32_e32 v96, 0, v101
	v_mul_f32_e32 v101, v97, v97
	v_max_f32_e32 v97, 0, v102
	v_mul_f32_e32 v102, v98, v98
	v_max_f32_e32 v98, 0, v103
	v_mul_f32_e32 v96, v96, v96
	v_mul_f32_e32 v97, v97, v97
	v_mul_f32_e32 v98, v98, v98
	v_mul_f32_e32 v99, v99, v99
	v_mul_f32_e32 v100, v100, v100
	v_cvt_pk_bf16_f32 v96, v100, v96
	v_cvt_pk_bf16_f32 v97, v97, v98
	v_cvt_pk_bf16_f32 v98, v104, v101
	v_cvt_pk_bf16_f32 v99, v102, v99
	global_store_dwordx4 v[112:113], v[96:99], off offset:256
	s_nop 1
	v_mov_b64_e32 v[98:99], v[210:211]
	v_cvt_f64_u32_e32 v[100:101], v99
	v_ldexp_f64 v[100:101], v[100:101], 32
	v_cvt_f64_u32_e32 v[98:99], v98
	v_add_f64 v[98:99], v[100:101], v[98:99]
	v_ldexp_f64 v[98:99], v[98:99], s93
	v_cvt_f32_f64_e32 v98, v[98:99]
	v_fmamk_f32 v98, v98, 0x3a000000, v189
	v_cmp_gt_f32_e32 vcc, s78, v98
	v_mul_f32_e32 v99, 0x4b800000, v98
	v_or_b32_e32 v96, 32, v142
	v_cndmask_b32_e32 v98, v98, v99, vcc
	v_rsq_f32_e32 v98, v98
	v_ashrrev_i32_e32 v97, 31, v96
	v_lshlrev_b64 v[96:97], 14, v[96:97]
	v_lshl_add_u64 v[96:97], s[14:15], 0, v[96:97]
	v_mul_f32_e32 v99, 0x45800000, v98
	v_cndmask_b32_e32 v98, v98, v99, vcc
	v_pk_mul_f32 v[88:89], v[88:89], v[98:99] op_sel_hi:[1,0]
	v_pk_mul_f32 v[92:93], v[92:93], v[98:99] op_sel_hi:[1,0]
	v_pk_mul_f32 v[90:91], v[90:91], v[98:99] op_sel_hi:[1,0]
	v_max_f32_e32 v88, 0, v88
	v_pk_mul_f32 v[94:95], v[94:95], v[98:99] op_sel_hi:[1,0]
	v_mul_f32_e32 v99, v88, v88
	v_max_f32_e32 v88, 0, v93
	v_max_f32_e32 v89, 0, v89
	v_max_f32_e32 v90, 0, v90
	v_max_f32_e32 v92, 0, v92
	v_mul_f32_e32 v88, v88, v88
	v_mul_f32_e32 v93, v89, v89
	v_max_f32_e32 v89, 0, v94
	v_mul_f32_e32 v94, v90, v90
	v_max_f32_e32 v90, 0, v95
	v_max_f32_e32 v91, 0, v91
	v_pk_mul_f32 v[82:83], v[82:83], v[98:99] op_sel_hi:[1,0]
	v_pk_mul_f32 v[80:81], v[80:81], v[98:99] op_sel_hi:[1,0]
	v_lshl_add_u64 v[96:97], v[96:97], 0, v[144:145]
	v_mul_f32_e32 v92, v92, v92
	v_mul_f32_e32 v89, v89, v89
	v_mul_f32_e32 v90, v90, v90
	v_mul_f32_e32 v91, v91, v91
	v_cvt_pk_bf16_f32 v88, v92, v88
	v_pk_mul_f32 v[86:87], v[86:87], v[98:99] op_sel_hi:[1,0]
	v_pk_mul_f32 v[84:85], v[84:85], v[98:99] op_sel_hi:[1,0]
	v_max_f32_e32 v80, 0, v80
	v_max_f32_e32 v81, 0, v81
	v_max_f32_e32 v82, 0, v82
	v_cvt_pk_bf16_f32 v89, v89, v90
	v_cvt_pk_bf16_f32 v90, v99, v93
	v_cvt_pk_bf16_f32 v91, v94, v91
	global_store_dwordx4 v[96:97], v[88:91], off
	v_max_f32_e32 v83, 0, v83
	v_max_f32_e32 v84, 0, v84
	v_mul_f32_e32 v88, v80, v80
	v_max_f32_e32 v80, 0, v85
	v_mul_f32_e32 v85, v81, v81
	v_max_f32_e32 v81, 0, v86
	v_mul_f32_e32 v86, v82, v82
	v_max_f32_e32 v82, 0, v87
	v_mul_f32_e32 v80, v80, v80
	v_mul_f32_e32 v81, v81, v81
	v_mul_f32_e32 v82, v82, v82
	v_mul_f32_e32 v83, v83, v83
	v_mul_f32_e32 v84, v84, v84
	v_cvt_pk_bf16_f32 v80, v84, v80
	v_cvt_pk_bf16_f32 v81, v81, v82
	v_cvt_pk_bf16_f32 v82, v88, v85
	v_cvt_pk_bf16_f32 v83, v86, v83
	global_store_dwordx4 v[96:97], v[80:83], off offset:256
	s_nop 1
	v_mov_b64_e32 v[82:83], v[212:213]
; __device__ __forceinline__ unsigned cvt_pk_bf16(float lo, float hi) { unsigned r; asm volatile("v_cvt_pk_bf16_f32 %0, %1, %2" : "=v"(r) : "v"(lo), "v"(hi)); return r; }
; __device__ __forceinline__ float rinv_st(stat_t s, float invn) { return rsqrtf((float)((double)s * (1.0 / 4294967296.0)) * invn + 1e-6f); }
;     __device__ __forceinline__ void operator()(const f32x4 (&acc)[2][2][4][2], const Unit& u, int wr, int wc, int fr, int fq) const {
;     ...
;             for (int m = 0; m < 4; ++m) {
;                 const int row = row0 + ai * HALF + m * 16; const float r = rinv_st(stats[row], 1.0f / 2048.0f);
;                 bf16_t* rowp = U + (size_t)row * FF + col0;
; #pragma unroll
;                 for (int bj = 0; bj < 2; ++bj) {
;                     f32x4 v0 = acc[ai][bj][m][0] * r, v1 = acc[ai][bj][m][1] * r;
; #pragma unroll
;                     for (int j = 0; j < 4; ++j) { const float a = fmaxf(v0[j], 0.f), b = fmaxf(v1[j], 0.f); v0[j] = a * a; v1[j] = b * b; }
;                     u32x4 w; w.x = cvt_pk_bf16(v0[0], v0[1]); w.y = cvt_pk_bf16(v0[2], v0[3]); w.z = cvt_pk_bf16(v1[0], v1[1]); w.w = cvt_pk_bf16(v1[2], v1[3]);
;                     *(u32x4*)(rowp + bj * HALF) = w;
;                 }
	v_cvt_f64_u32_e32 v[84:85], v83
	v_ldexp_f64 v[84:85], v[84:85], 32
	v_cvt_f64_u32_e32 v[82:83], v82
	v_add_f64 v[82:83], v[84:85], v[82:83]
	v_ldexp_f64 v[82:83], v[82:83], s93
	v_cvt_f32_f64_e32 v82, v[82:83]
	v_fmamk_f32 v82, v82, 0x3a000000, v189
	v_cmp_gt_f32_e32 vcc, s78, v82
	v_mul_f32_e32 v83, 0x4b800000, v82
	v_or_b32_e32 v80, 48, v142
	v_cndmask_b32_e32 v82, v82, v83, vcc
	v_rsq_f32_e32 v82, v82
	v_ashrrev_i32_e32 v81, 31, v80
	v_lshlrev_b64 v[80:81], 14, v[80:81]
	v_lshl_add_u64 v[80:81], s[14:15], 0, v[80:81]
	v_mul_f32_e32 v83, 0x45800000, v82
	v_cndmask_b32_e32 v82, v82, v83, vcc
	v_pk_mul_f32 v[72:73], v[72:73], v[82:83] op_sel_hi:[1,0]
	v_pk_mul_f32 v[76:77], v[76:77], v[82:83] op_sel_hi:[1,0]
	v_pk_mul_f32 v[74:75], v[74:75], v[82:83] op_sel_hi:[1,0]
	v_max_f32_e32 v72, 0, v72
	v_pk_mul_f32 v[78:79], v[78:79], v[82:83] op_sel_hi:[1,0]
	v_mul_f32_e32 v83, v72, v72
	v_max_f32_e32 v72, 0, v77
	v_max_f32_e32 v73, 0, v73
	v_max_f32_e32 v74, 0, v74
	v_max_f32_e32 v76, 0, v76
	v_mul_f32_e32 v72, v72, v72
	v_mul_f32_e32 v77, v73, v73
	v_max_f32_e32 v73, 0, v78
	v_mul_f32_e32 v78, v74, v74
	v_max_f32_e32 v74, 0, v79
	v_max_f32_e32 v75, 0, v75
	v_pk_mul_f32 v[66:67], v[66:67], v[82:83] op_sel_hi:[1,0]
	v_pk_mul_f32 v[64:65], v[64:65], v[82:83] op_sel_hi:[1,0]
	v_lshl_add_u64 v[80:81], v[80:81], 0, v[144:145]
	v_mul_f32_e32 v76, v76, v76
	v_mul_f32_e32 v73, v73, v73
	v_mul_f32_e32 v74, v74, v74
	v_mul_f32_e32 v75, v75, v75
	v_cvt_pk_bf16_f32 v72, v76, v72
	v_pk_mul_f32 v[70:71], v[70:71], v[82:83] op_sel_hi:[1,0]
	v_pk_mul_f32 v[68:69], v[68:69], v[82:83] op_sel_hi:[1,0]
	v_max_f32_e32 v64, 0, v64
	v_max_f32_e32 v65, 0, v65
	v_max_f32_e32 v66, 0, v66
	v_cvt_pk_bf16_f32 v73, v73, v74
	v_cvt_pk_bf16_f32 v74, v83, v77
	v_cvt_pk_bf16_f32 v75, v78, v75
	global_store_dwordx4 v[80:81], v[72:75], off
	v_max_f32_e32 v67, 0, v67
	v_max_f32_e32 v68, 0, v68
	v_mul_f32_e32 v72, v64, v64
	v_max_f32_e32 v64, 0, v69
	v_mul_f32_e32 v69, v65, v65
	v_max_f32_e32 v65, 0, v70
	v_mul_f32_e32 v70, v66, v66
	v_max_f32_e32 v66, 0, v71
	v_mul_f32_e32 v64, v64, v64
	v_mul_f32_e32 v65, v65, v65
	v_mul_f32_e32 v66, v66, v66
	v_mul_f32_e32 v67, v67, v67
	v_mul_f32_e32 v68, v68, v68
	v_cvt_pk_bf16_f32 v64, v68, v64
	v_cvt_pk_bf16_f32 v65, v65, v66
	v_cvt_pk_bf16_f32 v66, v72, v69
	v_cvt_pk_bf16_f32 v67, v70, v67
	global_store_dwordx4 v[80:81], v[64:67], off offset:256
	s_nop 1
	v_mov_b64_e32 v[64:65], v[214:215]
	v_cvt_f64_u32_e32 v[66:67], v65
	v_ldexp_f64 v[66:67], v[66:67], 32
	v_cvt_f64_u32_e32 v[64:65], v64
	v_add_f64 v[64:65], v[66:67], v[64:65]
	v_ldexp_f64 v[64:65], v[64:65], s93
	v_cvt_f32_f64_e32 v64, v[64:65]
	v_fmamk_f32 v64, v64, 0x3a000000, v189
	v_cmp_gt_f32_e32 vcc, s78, v64
	v_mul_f32_e32 v65, 0x4b800000, v64
	s_nop 0
	v_cndmask_b32_e32 v64, v64, v65, vcc
	v_rsq_f32_e32 v64, v64
	s_nop 0
	v_mul_f32_e32 v65, 0x45800000, v64
	v_cndmask_b32_e32 v66, v64, v65, vcc
	v_pk_mul_f32 v[56:57], v[56:57], v[66:67] op_sel_hi:[1,0]
	v_pk_mul_f32 v[60:61], v[60:61], v[66:67] op_sel_hi:[1,0]
	v_pk_mul_f32 v[58:59], v[58:59], v[66:67] op_sel_hi:[1,0]
	v_max_f32_e32 v56, 0, v56
	v_pk_mul_f32 v[62:63], v[62:63], v[66:67] op_sel_hi:[1,0]
	v_max_f32_e32 v60, 0, v60
	v_mul_f32_e32 v67, v56, v56
	v_max_f32_e32 v56, 0, v61
	v_max_f32_e32 v57, 0, v57
	v_max_f32_e32 v58, 0, v58
	v_lshl_add_u64 v[64:65], v[140:141], 0, s[0:1]
	v_mul_f32_e32 v60, v60, v60
	v_mul_f32_e32 v56, v56, v56
	v_mul_f32_e32 v61, v57, v57
	v_max_f32_e32 v57, 0, v62
	v_mul_f32_e32 v62, v58, v58
	v_max_f32_e32 v58, 0, v63
	s_mov_b32 s0, 0x200000
	v_mul_f32_e32 v57, v57, v57
	v_max_f32_e32 v59, 0, v59
	v_mul_f32_e32 v58, v58, v58
	v_cvt_pk_bf16_f32 v56, v60, v56
	v_add_co_u32_e32 v60, vcc, s0, v140
	v_pk_mul_f32 v[50:51], v[50:51], v[66:67] op_sel_hi:[1,0]
	v_pk_mul_f32 v[48:49], v[48:49], v[66:67] op_sel_hi:[1,0]
	v_mul_f32_e32 v59, v59, v59
	v_cvt_pk_bf16_f32 v57, v57, v58
	v_cvt_pk_bf16_f32 v58, v67, v61
	v_addc_co_u32_e32 v61, vcc, 0, v141, vcc
	v_pk_mul_f32 v[54:55], v[54:55], v[66:67] op_sel_hi:[1,0]
	v_pk_mul_f32 v[52:53], v[52:53], v[66:67] op_sel_hi:[1,0]
	v_max_f32_e32 v48, 0, v48
	v_max_f32_e32 v49, 0, v49
	v_max_f32_e32 v50, 0, v50
	v_cvt_pk_bf16_f32 v59, v62, v59
	global_store_dwordx4 v[60:61], v[56:59], off
	v_max_f32_e32 v51, 0, v51
	v_max_f32_e32 v52, 0, v52
	v_mul_f32_e32 v56, v48, v48
	v_max_f32_e32 v48, 0, v53
	v_mul_f32_e32 v53, v49, v49
	v_max_f32_e32 v49, 0, v54
	v_mul_f32_e32 v54, v50, v50
	v_max_f32_e32 v50, 0, v55
	v_mul_f32_e32 v48, v48, v48
	v_mul_f32_e32 v49, v49, v49
	v_mul_f32_e32 v50, v50, v50
	v_mul_f32_e32 v51, v51, v51
	v_mul_f32_e32 v52, v52, v52
	v_cvt_pk_bf16_f32 v48, v52, v48
	v_cvt_pk_bf16_f32 v49, v49, v50
	v_cvt_pk_bf16_f32 v50, v56, v53
	v_cvt_pk_bf16_f32 v51, v54, v51
	global_store_dwordx4 v[64:65], v[48:51], off offset:256
	s_nop 1
	v_mov_b64_e32 v[48:49], v[216:217]
	s_mov_b64 s[0:1], 0x240000
	v_cvt_f64_u32_e32 v[50:51], v49
	v_ldexp_f64 v[50:51], v[50:51], 32
	v_cvt_f64_u32_e32 v[48:49], v48
	v_add_f64 v[48:49], v[50:51], v[48:49]
	v_ldexp_f64 v[48:49], v[48:49], s93
	v_cvt_f32_f64_e32 v48, v[48:49]
	v_fmamk_f32 v48, v48, 0x3a000000, v189
	v_cmp_gt_f32_e32 vcc, s78, v48
	v_mul_f32_e32 v49, 0x4b800000, v48
	s_nop 0
	v_cndmask_b32_e32 v48, v48, v49, vcc
	v_rsq_f32_e32 v48, v48
	s_nop 0
	v_mul_f32_e32 v49, 0x45800000, v48
	v_cndmask_b32_e32 v50, v48, v49, vcc
	v_pk_mul_f32 v[40:41], v[40:41], v[50:51] op_sel_hi:[1,0]
	v_pk_mul_f32 v[44:45], v[44:45], v[50:51] op_sel_hi:[1,0]
	v_pk_mul_f32 v[42:43], v[42:43], v[50:51] op_sel_hi:[1,0]
	v_max_f32_e32 v40, 0, v40
	v_pk_mul_f32 v[46:47], v[46:47], v[50:51] op_sel_hi:[1,0]
	v_max_f32_e32 v44, 0, v44
; __device__ __forceinline__ unsigned cvt_pk_bf16(float lo, float hi) { unsigned r; asm volatile("v_cvt_pk_bf16_f32 %0, %1, %2" : "=v"(r) : "v"(lo), "v"(hi)); return r; }
; __device__ __forceinline__ float rinv_st(stat_t s, float invn) { return rsqrtf((float)((double)s * (1.0 / 4294967296.0)) * invn + 1e-6f); }
;     __device__ __forceinline__ void operator()(const f32x4 (&acc)[2][2][4][2], const Unit& u, int wr, int wc, int fr, int fq) const {
;     ...
;             for (int m = 0; m < 4; ++m) {
;                 const int row = row0 + ai * HALF + m * 16; const float r = rinv_st(stats[row], 1.0f / 2048.0f);
;                 bf16_t* rowp = U + (size_t)row * FF + col0;
; #pragma unroll
;                 for (int bj = 0; bj < 2; ++bj) {
;                     f32x4 v0 = acc[ai][bj][m][0] * r, v1 = acc[ai][bj][m][1] * r;
; #pragma unroll
;                     for (int j = 0; j < 4; ++j) { const float a = fmaxf(v0[j], 0.f), b = fmaxf(v1[j], 0.f); v0[j] = a * a; v1[j] = b * b; }
;                     u32x4 w; w.x = cvt_pk_bf16(v0[0], v0[1]); w.y = cvt_pk_bf16(v0[2], v0[3]); w.z = cvt_pk_bf16(v1[0], v1[1]); w.w = cvt_pk_bf16(v1[2], v1[3]);
;                     *(u32x4*)(rowp + bj * HALF) = w;
;                 }
	v_mul_f32_e32 v51, v40, v40
	v_max_f32_e32 v40, 0, v45
	v_max_f32_e32 v41, 0, v41
	v_max_f32_e32 v42, 0, v42
	v_lshl_add_u64 v[48:49], v[140:141], 0, s[0:1]
	v_mul_f32_e32 v44, v44, v44
	v_mul_f32_e32 v40, v40, v40
	v_mul_f32_e32 v45, v41, v41
	v_max_f32_e32 v41, 0, v46
	v_mul_f32_e32 v46, v42, v42
	v_max_f32_e32 v42, 0, v47
	s_mov_b32 s0, 0x240000
	v_mul_f32_e32 v41, v41, v41
	v_max_f32_e32 v43, 0, v43
	v_mul_f32_e32 v42, v42, v42
	v_cvt_pk_bf16_f32 v40, v44, v40
	v_add_co_u32_e32 v44, vcc, s0, v140
	v_pk_mul_f32 v[34:35], v[34:35], v[50:51] op_sel_hi:[1,0]
	v_pk_mul_f32 v[32:33], v[32:33], v[50:51] op_sel_hi:[1,0]
	v_mul_f32_e32 v43, v43, v43
	v_cvt_pk_bf16_f32 v41, v41, v42
	v_cvt_pk_bf16_f32 v42, v51, v45
	v_addc_co_u32_e32 v45, vcc, 0, v141, vcc
	v_pk_mul_f32 v[38:39], v[38:39], v[50:51] op_sel_hi:[1,0]
	v_pk_mul_f32 v[36:37], v[36:37], v[50:51] op_sel_hi:[1,0]
	v_max_f32_e32 v32, 0, v32
	v_max_f32_e32 v33, 0, v33
	v_max_f32_e32 v34, 0, v34
	v_cvt_pk_bf16_f32 v43, v46, v43
	global_store_dwordx4 v[44:45], v[40:43], off
	v_max_f32_e32 v35, 0, v35
	v_max_f32_e32 v36, 0, v36
	v_mul_f32_e32 v40, v32, v32
	v_max_f32_e32 v32, 0, v37
	v_mul_f32_e32 v37, v33, v33
	v_max_f32_e32 v33, 0, v38
	v_mul_f32_e32 v38, v34, v34
	v_max_f32_e32 v34, 0, v39
	v_mul_f32_e32 v32, v32, v32
	v_mul_f32_e32 v33, v33, v33
	v_mul_f32_e32 v34, v34, v34
	v_mul_f32_e32 v35, v35, v35
	v_mul_f32_e32 v36, v36, v36
	v_cvt_pk_bf16_f32 v32, v36, v32
	v_cvt_pk_bf16_f32 v33, v33, v34
	v_cvt_pk_bf16_f32 v34, v40, v37
	v_cvt_pk_bf16_f32 v35, v38, v35
	global_store_dwordx4 v[48:49], v[32:35], off offset:256
	s_nop 1
	v_mov_b64_e32 v[32:33], v[218:219]
	s_mov_b64 s[0:1], 0x280000
	v_cvt_f64_u32_e32 v[34:35], v33
	v_ldexp_f64 v[34:35], v[34:35], 32
	v_cvt_f64_u32_e32 v[32:33], v32
	v_add_f64 v[32:33], v[34:35], v[32:33]
	v_ldexp_f64 v[32:33], v[32:33], s93
	v_cvt_f32_f64_e32 v32, v[32:33]
	v_fmamk_f32 v32, v32, 0x3a000000, v189
	v_cmp_gt_f32_e32 vcc, s78, v32
	v_mul_f32_e32 v33, 0x4b800000, v32
	s_nop 0
	v_cndmask_b32_e32 v32, v32, v33, vcc
	v_rsq_f32_e32 v32, v32
	s_nop 0
	v_mul_f32_e32 v33, 0x45800000, v32
	v_cndmask_b32_e32 v34, v32, v33, vcc
	v_pk_mul_f32 v[24:25], v[24:25], v[34:35] op_sel_hi:[1,0]
	v_pk_mul_f32 v[28:29], v[28:29], v[34:35] op_sel_hi:[1,0]
	v_pk_mul_f32 v[26:27], v[26:27], v[34:35] op_sel_hi:[1,0]
	v_max_f32_e32 v24, 0, v24
	v_pk_mul_f32 v[30:31], v[30:31], v[34:35] op_sel_hi:[1,0]
	v_max_f32_e32 v28, 0, v28
	v_mul_f32_e32 v35, v24, v24
	v_max_f32_e32 v24, 0, v29
	v_max_f32_e32 v25, 0, v25
	v_max_f32_e32 v26, 0, v26
	v_lshl_add_u64 v[32:33], v[140:141], 0, s[0:1]
	v_mul_f32_e32 v28, v28, v28
	v_mul_f32_e32 v24, v24, v24
	v_mul_f32_e32 v29, v25, v25
	v_max_f32_e32 v25, 0, v30
	v_mul_f32_e32 v30, v26, v26
	v_max_f32_e32 v26, 0, v31
	s_mov_b32 s0, 0x280000
	v_mul_f32_e32 v25, v25, v25
	v_max_f32_e32 v27, 0, v27
	v_mul_f32_e32 v26, v26, v26
	v_cvt_pk_bf16_f32 v24, v28, v24
	v_add_co_u32_e32 v28, vcc, s0, v140
	v_pk_mul_f32 v[18:19], v[18:19], v[34:35] op_sel_hi:[1,0]
	v_pk_mul_f32 v[16:17], v[16:17], v[34:35] op_sel_hi:[1,0]
	v_mul_f32_e32 v27, v27, v27
	v_cvt_pk_bf16_f32 v25, v25, v26
	v_cvt_pk_bf16_f32 v26, v35, v29
	v_addc_co_u32_e32 v29, vcc, 0, v141, vcc
	v_pk_mul_f32 v[22:23], v[22:23], v[34:35] op_sel_hi:[1,0]
	v_pk_mul_f32 v[20:21], v[20:21], v[34:35] op_sel_hi:[1,0]
	v_max_f32_e32 v16, 0, v16
	v_max_f32_e32 v17, 0, v17
	v_max_f32_e32 v18, 0, v18
	v_cvt_pk_bf16_f32 v27, v30, v27
	global_store_dwordx4 v[28:29], v[24:27], off
	v_max_f32_e32 v19, 0, v19
	v_max_f32_e32 v20, 0, v20
	v_mul_f32_e32 v24, v16, v16
	v_max_f32_e32 v16, 0, v21
	v_mul_f32_e32 v21, v17, v17
	v_max_f32_e32 v17, 0, v22
	v_mul_f32_e32 v22, v18, v18
	v_max_f32_e32 v18, 0, v23
	v_mul_f32_e32 v16, v16, v16
	v_mul_f32_e32 v17, v17, v17
	v_mul_f32_e32 v18, v18, v18
	v_mul_f32_e32 v19, v19, v19
	v_mul_f32_e32 v20, v20, v20
	v_cvt_pk_bf16_f32 v16, v20, v16
	v_cvt_pk_bf16_f32 v17, v17, v18
	v_cvt_pk_bf16_f32 v18, v24, v21
	v_cvt_pk_bf16_f32 v19, v22, v19
	global_store_dwordx4 v[32:33], v[16:19], off offset:256
	s_nop 1
	v_mov_b64_e32 v[16:17], v[220:221]
	s_mov_b64 s[0:1], 0x2c0000
	v_cvt_f64_u32_e32 v[18:19], v17
	v_ldexp_f64 v[18:19], v[18:19], 32
	v_cvt_f64_u32_e32 v[16:17], v16
	v_add_f64 v[16:17], v[18:19], v[16:17]
	v_ldexp_f64 v[16:17], v[16:17], s93
	v_cvt_f32_f64_e32 v16, v[16:17]
	v_fmamk_f32 v16, v16, 0x3a000000, v189
	v_cmp_gt_f32_e32 vcc, s78, v16
	v_mul_f32_e32 v17, 0x4b800000, v16
	v_lshl_add_u64 v[18:19], v[140:141], 0, s[0:1]
	v_cndmask_b32_e32 v16, v16, v17, vcc
	v_rsq_f32_e32 v16, v16
	s_mov_b32 s0, 0x2c0000
	v_mul_f32_e32 v17, 0x45800000, v16
	v_cndmask_b32_e32 v16, v16, v17, vcc
	v_pk_mul_f32 v[8:9], v[8:9], v[16:17] op_sel_hi:[1,0]
	v_pk_mul_f32 v[12:13], v[12:13], v[16:17] op_sel_hi:[1,0]
	v_pk_mul_f32 v[10:11], v[10:11], v[16:17] op_sel_hi:[1,0]
	v_max_f32_e32 v8, 0, v8
	v_pk_mul_f32 v[14:15], v[14:15], v[16:17] op_sel_hi:[1,0]
	v_max_f32_e32 v12, 0, v12
	v_mul_f32_e32 v17, v8, v8
	v_max_f32_e32 v8, 0, v13
	v_max_f32_e32 v9, 0, v9
	v_max_f32_e32 v10, 0, v10
	v_mul_f32_e32 v12, v12, v12
	v_mul_f32_e32 v8, v8, v8
	v_mul_f32_e32 v13, v9, v9
	v_max_f32_e32 v9, 0, v14
	v_mul_f32_e32 v14, v10, v10
	v_max_f32_e32 v10, 0, v15
	v_mul_f32_e32 v9, v9, v9
	v_max_f32_e32 v11, 0, v11
	v_mul_f32_e32 v10, v10, v10
	v_cvt_pk_bf16_f32 v8, v12, v8
	v_add_co_u32_e32 v12, vcc, s0, v140
	v_pk_mul_f32 v[2:3], v[2:3], v[16:17] op_sel_hi:[1,0]
	v_pk_mul_f32 v[0:1], v[0:1], v[16:17] op_sel_hi:[1,0]
	v_mul_f32_e32 v11, v11, v11
	v_cvt_pk_bf16_f32 v9, v9, v10
	v_cvt_pk_bf16_f32 v10, v17, v13
	v_addc_co_u32_e32 v13, vcc, 0, v141, vcc
	v_pk_mul_f32 v[6:7], v[6:7], v[16:17] op_sel_hi:[1,0]
	v_pk_mul_f32 v[4:5], v[4:5], v[16:17] op_sel_hi:[1,0]
	v_max_f32_e32 v0, 0, v0
	v_max_f32_e32 v1, 0, v1
	v_max_f32_e32 v2, 0, v2
	v_cvt_pk_bf16_f32 v11, v14, v11
	global_store_dwordx4 v[12:13], v[8:11], off
	v_max_f32_e32 v3, 0, v3
	v_max_f32_e32 v4, 0, v4
	v_mul_f32_e32 v8, v0, v0
	v_max_f32_e32 v0, 0, v5
	v_mul_f32_e32 v5, v1, v1
	v_max_f32_e32 v1, 0, v6
	v_mul_f32_e32 v6, v2, v2
	v_max_f32_e32 v2, 0, v7
	v_mul_f32_e32 v0, v0, v0
	v_mul_f32_e32 v1, v1, v1
	v_mul_f32_e32 v2, v2, v2
	v_mul_f32_e32 v3, v3, v3
	s_and_b64 vcc, exec, s[8:9]
	s_mov_b32 s0, s16
	v_mul_f32_e32 v4, v4, v4
	v_cvt_pk_bf16_f32 v0, v4, v0
	v_cvt_pk_bf16_f32 v1, v1, v2
	v_cvt_pk_bf16_f32 v2, v8, v5
	v_cvt_pk_bf16_f32 v3, v6, v3
	global_store_dwordx4 v[18:19], v[0:3], off offset:256
	s_cbranch_vccz .LBB0_918
	s_waitcnt vmcnt(0)
	s_cmpk_gt_u32 s42, 0xff
	s_cbranch_scc1 .LBB0_929
	s_barrier
